# v013 + EpiPlain GEMM loop skips the bj=1 MFMA blocks for the GLA gate column tile (only its first 32 columns are ever stored)
# speedup vs baseline: 1.0046x; 1.0046x over previous
; #define PG8_STAGE(bufoff, gbase, voff) do { _Pragma("unroll") for (int _i = 0; _i < 2; ++_i) \
;         __builtin_amdgcn_global_load_lds((const unsigned*)((const char*)(gbase) + (voff)[_i]), (PG8_LAS unsigned*)(lds + (bufoff) + ldsw + _i * 8192), 16, 0, 0); } while (0)
; #define PG8_LDA(dst, b, h) do { _Pragma("unroll") for (int m = 0; m < 4; ++m) _Pragma("unroll") for (int k = 0; k < 2; ++k) dst[m][k] = *(const PG8_LAS bf16x8*)(lds + PG8_SA(b, h) + aoff + m * 2048 + k * 1024); } while (0)
; #define PG8_LDB(dst, b, h) do { _Pragma("unroll") for (int n = 0; n < 2; ++n) _Pragma("unroll") for (int k = 0; k < 2; ++k) dst[n][k] = *(const PG8_LAS bf16x8*)(lds + PG8_SB(b, h) + boff + n * 2048 + k * 1024); } while (0)
; #define PG8_WAIT_V(n) asm volatile("s_waitcnt vmcnt(" #n ")" ::: "memory")
; #define PG8_WAIT_L(n) asm volatile("s_waitcnt lgkmcnt(" #n ")" ::: "memory")
; #define PG8_BAR __builtin_amdgcn_s_barrier()
; #define PG8_SCHED __builtin_amdgcn_sched_barrier(0)
; template <class Epi, class Sched, bool ALIGN_EPI = false, bool SP2 = false>
; __device__ __forceinline__ void gemm_phase(PG8_LAS unsigned char* lds, const Gemm g, const Sched& S, const Epi& E) {
;     ...
;         for (int t = 0; t < nt; t += 2) {
;             const bool last = (t == nt - 2);
;             const char* a1 = cA + (size_t)(t + 1) * kstep;
;             const char* a2 = last ? nA : cA + (size_t)(t + 2) * kstep; const char* b2 = last ? nB : cB + (size_t)(t + 2) * kstep;
;             const char* a3 = a2 + kstep; const char* b3 = b2 + kstep;
;             if (last && has_next) S.a_ready(nxt);
;             if constexpr (SP2) {
;             PG8_LDB(B0, 0, 0); PG8_LDB(B1, 0, 1); PG8_SCHED; PG8_LDA(At, 0, 0); PG8_STAGE(PG8_SA(1, 1), a1 + hstep, voffA);
;             PG8_WAIT_V(8); PG8_WAIT_L(0); PG8_BAR; PG8_MMA(0, 0, At, B0); PG8_MMA(0, 1, At, B1); PG8_BAR; PG8_SCHED;
;             PG8_LDA(At, 0, 1); PG8_STAGE(PG8_SB(0, 0), b2, voffB); PG8_STAGE(PG8_SB(0, 1), b2 + hstep, voffB); PG8_STAGE(PG8_SA(0, 0), a2, voffA);
;             PG8_WAIT_V(8); PG8_WAIT_L(0); PG8_BAR; PG8_MMA(1, 0, At, B0); PG8_MMA(1, 1, At, B1); PG8_BAR; PG8_SCHED;
;             PG8_LDB(B0, 1, 0); PG8_LDB(B1, 1, 1); PG8_SCHED; PG8_LDA(At, 1, 0); PG8_STAGE(PG8_SA(0, 1), a2 + hstep, voffA);
;             PG8_WAIT_V(8); PG8_WAIT_L(0); PG8_BAR; PG8_MMA(0, 0, At, B0); PG8_MMA(0, 1, At, B1); PG8_BAR; PG8_SCHED;
.LBB0_639:
	s_add_i32 s73, s10, 2
	s_add_u32 s4, s2, 0x80
	s_addc_u32 s5, s3, 0
	s_add_i32 s76, 0, 0x10000
	s_cmp_eq_u32 s66, s10
	s_cselect_b32 s11, s37, s5
	s_cselect_b32 s10, s36, s4
	s_cselect_b32 s75, s53, s72
	s_cselect_b32 s74, s52, s34
	s_add_i32 s4, 0, 0x14000
	v_add_u32_e32 v168, s76, v157
	v_add_u32_e32 v184, s4, v157
	ds_read_b128 v[142:145], v168
	ds_read_b128 v[160:163], v168 offset:1024
	ds_read_b128 v[164:167], v168 offset:2048
	ds_read_b128 v[168:171], v168 offset:3072
	ds_read_b128 v[172:175], v184
	ds_read_b128 v[176:179], v184 offset:1024
	ds_read_b128 v[180:183], v184 offset:2048
	ds_read_b128 v[184:187], v184 offset:3072
	v_lshl_add_u64 v[200:201], s[2:3], 0, v[138:139]
	s_add_i32 m0, s60, 0xc000
	ds_read_b128 v[188:191], v159
	ds_read_b128 v[192:195], v159 offset:1024
	ds_read_b128 v[196:199], v159 offset:2048
	ds_read_b128 v[214:217], v159 offset:3072
	ds_read_b128 v[218:221], v159 offset:4096
	ds_read_b128 v[222:225], v159 offset:5120
	ds_read_b128 v[226:229], v159 offset:6144
	ds_read_b128 v[230:233], v159 offset:7168
	global_load_lds_dwordx4 v[200:201], off
	v_lshl_add_u64 v[200:201], s[2:3], 0, v[140:141]
	s_add_i32 m0, s60, 0xe000
	s_nop 0
	global_load_lds_dwordx4 v[200:201], off
	s_waitcnt vmcnt(8)
	s_waitcnt lgkmcnt(0)
	s_barrier
	s_setprio 1
	s_waitcnt lgkmcnt(0)
	v_mfma_f32_16x16x32_bf16 v[126:129], v[142:145], v[188:191], v[126:129]
	v_mfma_f32_16x16x32_bf16 v[122:125], v[164:167], v[188:191], v[122:125]
	v_mfma_f32_16x16x32_bf16 v[118:121], v[142:145], v[196:199], v[118:121]
	v_mfma_f32_16x16x32_bf16 v[110:113], v[164:167], v[196:199], v[110:113]
	v_mfma_f32_16x16x32_bf16 v[102:105], v[142:145], v[218:221], v[102:105]
	v_mfma_f32_16x16x32_bf16 v[94:97], v[164:167], v[218:221], v[94:97]
	v_mfma_f32_16x16x32_bf16 v[86:89], v[142:145], v[226:229], v[86:89]
	v_mfma_f32_16x16x32_bf16 v[78:81], v[164:167], v[226:229], v[78:81]
	v_mfma_f32_16x16x32_bf16 v[126:129], v[160:163], v[192:195], v[126:129]
	v_mfma_f32_16x16x32_bf16 v[122:125], v[168:171], v[192:195], v[122:125]
	v_mfma_f32_16x16x32_bf16 v[118:121], v[160:163], v[214:217], v[118:121]
	v_mfma_f32_16x16x32_bf16 v[110:113], v[168:171], v[214:217], v[110:113]
	v_mfma_f32_16x16x32_bf16 v[102:105], v[160:163], v[222:225], v[102:105]
	v_mfma_f32_16x16x32_bf16 v[94:97], v[168:171], v[222:225], v[94:97]
	v_mfma_f32_16x16x32_bf16 v[86:89], v[160:163], v[230:233], v[86:89]
	v_mfma_f32_16x16x32_bf16 v[78:81], v[168:171], v[230:233], v[78:81]
	s_setprio 0
	s_lshl_b32 s98, s70, 8
	s_cmp_ge_i32 s98, s35
	s_cbranch_scc1 .Lgate_skip_0
	s_setprio 1
	v_mfma_f32_16x16x32_bf16 v[114:117], v[172:175], v[188:191], v[114:117]
	v_mfma_f32_16x16x32_bf16 v[106:109], v[180:183], v[188:191], v[106:109]
	v_mfma_f32_16x16x32_bf16 v[98:101], v[172:175], v[196:199], v[98:101]
	v_mfma_f32_16x16x32_bf16 v[90:93], v[180:183], v[196:199], v[90:93]
	v_mfma_f32_16x16x32_bf16 v[82:85], v[172:175], v[218:221], v[82:85]
	v_mfma_f32_16x16x32_bf16 v[74:77], v[180:183], v[218:221], v[74:77]
	v_mfma_f32_16x16x32_bf16 v[70:73], v[172:175], v[226:229], v[70:73]
	v_mfma_f32_16x16x32_bf16 v[66:69], v[180:183], v[226:229], v[66:69]
	v_mfma_f32_16x16x32_bf16 v[114:117], v[176:179], v[192:195], v[114:117]
	v_mfma_f32_16x16x32_bf16 v[106:109], v[184:187], v[192:195], v[106:109]
	v_mfma_f32_16x16x32_bf16 v[98:101], v[176:179], v[214:217], v[98:101]
	v_mfma_f32_16x16x32_bf16 v[90:93], v[184:187], v[214:217], v[90:93]
	v_mfma_f32_16x16x32_bf16 v[82:85], v[176:179], v[222:225], v[82:85]
	v_mfma_f32_16x16x32_bf16 v[74:77], v[184:187], v[222:225], v[74:77]
	v_mfma_f32_16x16x32_bf16 v[70:73], v[176:179], v[230:233], v[70:73]
	v_mfma_f32_16x16x32_bf16 v[66:69], v[184:187], v[230:233], v[66:69]
.Lgate_skip_0:
	s_setprio 0
	s_barrier
	s_add_i32 s5, s76, s55
	v_lshl_add_u64 v[200:201], s[74:75], 0, v[0:1]
	s_mov_b32 m0, s5
	ds_read_b128 v[188:191], v159 offset:16384
	ds_read_b128 v[192:195], v159 offset:17408
	ds_read_b128 v[196:199], v159 offset:18432
	ds_read_b128 v[214:217], v159 offset:19456
	ds_read_b128 v[218:221], v159 offset:20480
	ds_read_b128 v[222:225], v159 offset:21504
	ds_read_b128 v[226:229], v159 offset:22528
	ds_read_b128 v[230:233], v159 offset:23552
	global_load_lds_dwordx4 v[200:201], off
	s_add_i32 m0, s5, 0x2000
	v_lshl_add_u64 v[234:235], s[74:75], 0, v[130:131]
	s_add_u32 s74, s74, s78
	s_addc_u32 s75, s75, 0
	s_add_i32 s4, s4, s55
	global_load_lds_dwordx4 v[234:235], off
	v_lshl_add_u64 v[236:237], s[74:75], 0, v[0:1]
	s_mov_b32 m0, s4
	v_lshl_add_u64 v[238:239], s[74:75], 0, v[130:131]
	global_load_lds_dwordx4 v[236:237], off
	s_add_i32 m0, s4, 0x2000
	v_lshl_add_u64 v[240:241], s[10:11], 0, v[134:135]
	global_load_lds_dwordx4 v[238:239], off
	s_mov_b32 m0, s60
	v_lshl_add_u64 v[242:243], s[10:11], 0, v[132:133]
	global_load_lds_dwordx4 v[240:241], off
	s_mov_b32 m0, s61
	s_nop 0
	global_load_lds_dwordx4 v[242:243], off
	s_waitcnt vmcnt(8)
	s_waitcnt lgkmcnt(0)
	s_barrier
	s_setprio 1
	s_waitcnt lgkmcnt(0)
	v_mfma_f32_16x16x32_bf16 v[62:65], v[142:145], v[188:191], v[62:65]
	v_mfma_f32_16x16x32_bf16 v[58:61], v[164:167], v[188:191], v[58:61]
	v_mfma_f32_16x16x32_bf16 v[54:57], v[142:145], v[196:199], v[54:57]
	v_mfma_f32_16x16x32_bf16 v[46:49], v[164:167], v[196:199], v[46:49]
	v_mfma_f32_16x16x32_bf16 v[38:41], v[142:145], v[218:221], v[38:41]
	v_mfma_f32_16x16x32_bf16 v[30:33], v[164:167], v[218:221], v[30:33]
	v_mfma_f32_16x16x32_bf16 v[22:25], v[142:145], v[226:229], v[22:25]
	v_mfma_f32_16x16x32_bf16 v[14:17], v[164:167], v[226:229], v[14:17]
	v_mfma_f32_16x16x32_bf16 v[62:65], v[160:163], v[192:195], v[62:65]
	v_mfma_f32_16x16x32_bf16 v[58:61], v[168:171], v[192:195], v[58:61]
	v_mfma_f32_16x16x32_bf16 v[54:57], v[160:163], v[214:217], v[54:57]
	v_mfma_f32_16x16x32_bf16 v[46:49], v[168:171], v[214:217], v[46:49]
	v_mfma_f32_16x16x32_bf16 v[38:41], v[160:163], v[222:225], v[38:41]
	v_mfma_f32_16x16x32_bf16 v[30:33], v[168:171], v[222:225], v[30:33]
	v_mfma_f32_16x16x32_bf16 v[22:25], v[160:163], v[230:233], v[22:25]
	v_mfma_f32_16x16x32_bf16 v[14:17], v[168:171], v[230:233], v[14:17]
	s_setprio 0
	s_lshl_b32 s98, s70, 8
	s_cmp_ge_i32 s98, s35
	s_cbranch_scc1 .Lgate_skip_1
; #define PG8_STAGE(bufoff, gbase, voff) do { _Pragma("unroll") for (int _i = 0; _i < 2; ++_i) \
;         __builtin_amdgcn_global_load_lds((const unsigned*)((const char*)(gbase) + (voff)[_i]), (PG8_LAS unsigned*)(lds + (bufoff) + ldsw + _i * 8192), 16, 0, 0); } while (0)
; #define PG8_LDA(dst, b, h) do { _Pragma("unroll") for (int m = 0; m < 4; ++m) _Pragma("unroll") for (int k = 0; k < 2; ++k) dst[m][k] = *(const PG8_LAS bf16x8*)(lds + PG8_SA(b, h) + aoff + m * 2048 + k * 1024); } while (0)
; #define PG8_LDB(dst, b, h) do { _Pragma("unroll") for (int n = 0; n < 2; ++n) _Pragma("unroll") for (int k = 0; k < 2; ++k) dst[n][k] = *(const PG8_LAS bf16x8*)(lds + PG8_SB(b, h) + boff + n * 2048 + k * 1024); } while (0)
; #define PG8_MMA(ai, bj, At, Bt) do { __builtin_amdgcn_s_setprio(1); _Pragma("unroll") for (int m = 0; m < 4; ++m) _Pragma("unroll") for (int n = 0; n < 2; ++n) _Pragma("unroll") for (int k = 0; k < 2; ++k) \
;         acc[ai][bj][m][n] = __builtin_amdgcn_mfma_f32_16x16x32_bf16(Bt[n][k], At[m][k], acc[ai][bj][m][n], 0, 0, 0); __builtin_amdgcn_s_setprio(0); } while (0)
; #define PG8_WAIT_V(n) asm volatile("s_waitcnt vmcnt(" #n ")" ::: "memory")
; #define PG8_WAIT_L(n) asm volatile("s_waitcnt lgkmcnt(" #n ")" ::: "memory")
; #define PG8_BAR __builtin_amdgcn_s_barrier()
; #define PG8_SCHED __builtin_amdgcn_sched_barrier(0)
; template <class Epi, class Sched, bool ALIGN_EPI = false, bool SP2 = false>
; __device__ __forceinline__ void gemm_phase(PG8_LAS unsigned char* lds, const Gemm g, const Sched& S, const Epi& E) {
;     ...
;             PG8_LDB(B0, 1, 0); PG8_LDB(B1, 1, 1); PG8_SCHED; PG8_LDA(At, 1, 0); PG8_STAGE(PG8_SA(0, 1), a2 + hstep, voffA);
;             PG8_WAIT_V(8); PG8_WAIT_L(0); PG8_BAR; PG8_MMA(0, 0, At, B0); PG8_MMA(0, 1, At, B1); PG8_BAR; PG8_SCHED;
;             PG8_LDA(At, 1, 1); PG8_STAGE(PG8_SB(1, 0), b3, voffB); PG8_STAGE(PG8_SB(1, 1), b3 + hstep, voffB); PG8_STAGE(PG8_SA(1, 0), a3, voffA);
	s_setprio 1
	v_mfma_f32_16x16x32_bf16 v[50:53], v[172:175], v[188:191], v[50:53]
	v_mfma_f32_16x16x32_bf16 v[42:45], v[180:183], v[188:191], v[42:45]
	v_mfma_f32_16x16x32_bf16 v[34:37], v[172:175], v[196:199], v[34:37]
	v_mfma_f32_16x16x32_bf16 v[26:29], v[180:183], v[196:199], v[26:29]
	v_mfma_f32_16x16x32_bf16 v[18:21], v[172:175], v[218:221], v[18:21]
	v_mfma_f32_16x16x32_bf16 v[10:13], v[180:183], v[218:221], v[10:13]
	v_mfma_f32_16x16x32_bf16 v[6:9], v[172:175], v[226:229], v[6:9]
	v_mfma_f32_16x16x32_bf16 v[2:5], v[180:183], v[226:229], v[2:5]
	v_mfma_f32_16x16x32_bf16 v[50:53], v[176:179], v[192:195], v[50:53]
	v_mfma_f32_16x16x32_bf16 v[42:45], v[184:187], v[192:195], v[42:45]
	v_mfma_f32_16x16x32_bf16 v[34:37], v[176:179], v[214:217], v[34:37]
	v_mfma_f32_16x16x32_bf16 v[26:29], v[184:187], v[214:217], v[26:29]
	v_mfma_f32_16x16x32_bf16 v[18:21], v[176:179], v[222:225], v[18:21]
	v_mfma_f32_16x16x32_bf16 v[10:13], v[184:187], v[222:225], v[10:13]
	v_mfma_f32_16x16x32_bf16 v[6:9], v[176:179], v[230:233], v[6:9]
	v_mfma_f32_16x16x32_bf16 v[2:5], v[184:187], v[230:233], v[2:5]
.Lgate_skip_1:
	s_setprio 0
	s_barrier
	s_add_i32 s4, 0, 0x18000
	v_add_u32_e32 v168, s4, v157
	v_add_u32_e32 v184, s29, v157
	ds_read_b128 v[142:145], v168
	ds_read_b128 v[160:163], v168 offset:1024
	ds_read_b128 v[164:167], v168 offset:2048
	ds_read_b128 v[168:171], v168 offset:3072
	ds_read_b128 v[172:175], v184
	ds_read_b128 v[176:179], v184 offset:1024
	ds_read_b128 v[180:183], v184 offset:2048
	ds_read_b128 v[184:187], v184 offset:3072
	s_add_u32 s10, s10, s78
	s_addc_u32 s11, s11, 0
	s_mov_b32 m0, s62
	v_lshl_add_u64 v[244:245], s[10:11], 0, v[134:135]
	ds_read_b128 v[188:191], v159 offset:32768
	ds_read_b128 v[192:195], v159 offset:33792
	ds_read_b128 v[196:199], v159 offset:34816
	ds_read_b128 v[214:217], v159 offset:35840
	ds_read_b128 v[218:221], v159 offset:36864
	ds_read_b128 v[222:225], v159 offset:37888
	ds_read_b128 v[226:229], v159 offset:38912
	ds_read_b128 v[230:233], v159 offset:39936
	global_load_lds_dwordx4 v[244:245], off
	v_lshl_add_u64 v[244:245], s[10:11], 0, v[132:133]
	s_mov_b32 m0, s63
	s_nop 0
	global_load_lds_dwordx4 v[244:245], off
	s_waitcnt vmcnt(8)
	s_waitcnt lgkmcnt(0)
	s_barrier
	s_setprio 1
	s_waitcnt lgkmcnt(0)
	v_mfma_f32_16x16x32_bf16 v[126:129], v[142:145], v[188:191], v[126:129]
	v_mfma_f32_16x16x32_bf16 v[122:125], v[164:167], v[188:191], v[122:125]
	v_mfma_f32_16x16x32_bf16 v[118:121], v[142:145], v[196:199], v[118:121]
	v_mfma_f32_16x16x32_bf16 v[110:113], v[164:167], v[196:199], v[110:113]
	v_mfma_f32_16x16x32_bf16 v[102:105], v[142:145], v[218:221], v[102:105]
	v_mfma_f32_16x16x32_bf16 v[94:97], v[164:167], v[218:221], v[94:97]
	v_mfma_f32_16x16x32_bf16 v[86:89], v[142:145], v[226:229], v[86:89]
	v_mfma_f32_16x16x32_bf16 v[78:81], v[164:167], v[226:229], v[78:81]
	v_mfma_f32_16x16x32_bf16 v[126:129], v[160:163], v[192:195], v[126:129]
	v_mfma_f32_16x16x32_bf16 v[122:125], v[168:171], v[192:195], v[122:125]
	v_mfma_f32_16x16x32_bf16 v[118:121], v[160:163], v[214:217], v[118:121]
	v_mfma_f32_16x16x32_bf16 v[110:113], v[168:171], v[214:217], v[110:113]
	v_mfma_f32_16x16x32_bf16 v[102:105], v[160:163], v[222:225], v[102:105]
	v_mfma_f32_16x16x32_bf16 v[94:97], v[168:171], v[222:225], v[94:97]
	v_mfma_f32_16x16x32_bf16 v[86:89], v[160:163], v[230:233], v[86:89]
	v_mfma_f32_16x16x32_bf16 v[78:81], v[168:171], v[230:233], v[78:81]
	s_setprio 0
	s_lshl_b32 s98, s70, 8
	s_cmp_ge_i32 s98, s35
	s_cbranch_scc1 .Lgate_skip_2
	s_setprio 1
	v_mfma_f32_16x16x32_bf16 v[114:117], v[172:175], v[188:191], v[114:117]
	v_mfma_f32_16x16x32_bf16 v[106:109], v[180:183], v[188:191], v[106:109]
	v_mfma_f32_16x16x32_bf16 v[98:101], v[172:175], v[196:199], v[98:101]
	v_mfma_f32_16x16x32_bf16 v[90:93], v[180:183], v[196:199], v[90:93]
	v_mfma_f32_16x16x32_bf16 v[82:85], v[172:175], v[218:221], v[82:85]
	v_mfma_f32_16x16x32_bf16 v[74:77], v[180:183], v[218:221], v[74:77]
	v_mfma_f32_16x16x32_bf16 v[70:73], v[172:175], v[226:229], v[70:73]
	v_mfma_f32_16x16x32_bf16 v[66:69], v[180:183], v[226:229], v[66:69]
	v_mfma_f32_16x16x32_bf16 v[114:117], v[176:179], v[192:195], v[114:117]
	v_mfma_f32_16x16x32_bf16 v[106:109], v[184:187], v[192:195], v[106:109]
	v_mfma_f32_16x16x32_bf16 v[98:101], v[176:179], v[214:217], v[98:101]
	v_mfma_f32_16x16x32_bf16 v[90:93], v[184:187], v[214:217], v[90:93]
	v_mfma_f32_16x16x32_bf16 v[82:85], v[176:179], v[222:225], v[82:85]
	v_mfma_f32_16x16x32_bf16 v[74:77], v[184:187], v[222:225], v[74:77]
	v_mfma_f32_16x16x32_bf16 v[70:73], v[176:179], v[230:233], v[70:73]
	v_mfma_f32_16x16x32_bf16 v[66:69], v[184:187], v[230:233], v[66:69]
; #define PG8_STAGE(bufoff, gbase, voff) do { _Pragma("unroll") for (int _i = 0; _i < 2; ++_i) \
;         __builtin_amdgcn_global_load_lds((const unsigned*)((const char*)(gbase) + (voff)[_i]), (PG8_LAS unsigned*)(lds + (bufoff) + ldsw + _i * 8192), 16, 0, 0); } while (0)
; #define PG8_LDA(dst, b, h) do { _Pragma("unroll") for (int m = 0; m < 4; ++m) _Pragma("unroll") for (int k = 0; k < 2; ++k) dst[m][k] = *(const PG8_LAS bf16x8*)(lds + PG8_SA(b, h) + aoff + m * 2048 + k * 1024); } while (0)
; #define PG8_MMA(ai, bj, At, Bt) do { __builtin_amdgcn_s_setprio(1); _Pragma("unroll") for (int m = 0; m < 4; ++m) _Pragma("unroll") for (int n = 0; n < 2; ++n) _Pragma("unroll") for (int k = 0; k < 2; ++k) \
;         acc[ai][bj][m][n] = __builtin_amdgcn_mfma_f32_16x16x32_bf16(Bt[n][k], At[m][k], acc[ai][bj][m][n], 0, 0, 0); __builtin_amdgcn_s_setprio(0); } while (0)
; #define PG8_WAIT_V(n) asm volatile("s_waitcnt vmcnt(" #n ")" ::: "memory")
; #define PG8_WAIT_L(n) asm volatile("s_waitcnt lgkmcnt(" #n ")" ::: "memory")
; #define PG8_BAR __builtin_amdgcn_s_barrier()
; #define PG8_SCHED __builtin_amdgcn_sched_barrier(0)
; template <class Epi, class Sched, bool ALIGN_EPI = false, bool SP2 = false>
; __device__ __forceinline__ void gemm_phase(PG8_LAS unsigned char* lds, const Gemm g, const Sched& S, const Epi& E) {
;     ...
;             PG8_LDA(At, 1, 1); PG8_STAGE(PG8_SB(1, 0), b3, voffB); PG8_STAGE(PG8_SB(1, 1), b3 + hstep, voffB); PG8_STAGE(PG8_SA(1, 0), a3, voffA);
;             PG8_WAIT_V(8); PG8_WAIT_L(0); PG8_BAR; PG8_MMA(1, 0, At, B0); PG8_MMA(1, 1, At, B1); PG8_BAR; PG8_SCHED;
.Lgate_skip_2:
	s_setprio 0
	s_barrier
	s_add_i32 s4, s4, s55
	v_lshl_add_u64 v[200:201], v[200:201], 0, s[30:31]
	s_mov_b32 m0, s4
	ds_read_b128 v[188:191], v159 offset:49152
	ds_read_b128 v[192:195], v159 offset:50176
	ds_read_b128 v[196:199], v159 offset:51200
	ds_read_b128 v[214:217], v159 offset:52224
	ds_read_b128 v[218:221], v159 offset:53248
	ds_read_b128 v[222:225], v159 offset:54272
	ds_read_b128 v[226:229], v159 offset:55296
	ds_read_b128 v[230:233], v159 offset:56320
	global_load_lds_dwordx4 v[200:201], off
	v_lshl_add_u64 v[200:201], v[234:235], 0, s[30:31]
	s_add_i32 m0, s4, 0x2000
	s_add_i32 s4, s29, s55
	global_load_lds_dwordx4 v[200:201], off
	v_lshl_add_u64 v[200:201], v[236:237], 0, s[30:31]
	s_mov_b32 m0, s4
	s_nop 0
	global_load_lds_dwordx4 v[200:201], off
	v_lshl_add_u64 v[200:201], v[238:239], 0, s[30:31]
	s_add_i32 m0, s4, 0x2000
	s_nop 0
	global_load_lds_dwordx4 v[200:201], off
	v_lshl_add_u64 v[200:201], v[240:241], 0, s[30:31]
	s_mov_b32 m0, s33
	s_nop 0
	global_load_lds_dwordx4 v[200:201], off
	v_lshl_add_u64 v[200:201], v[242:243], 0, s[30:31]
	s_mov_b32 m0, s65
	s_nop 0
	global_load_lds_dwordx4 v[200:201], off
	s_waitcnt vmcnt(8)
	s_waitcnt lgkmcnt(0)
	s_barrier
	s_setprio 1
	s_waitcnt lgkmcnt(0)
	v_mfma_f32_16x16x32_bf16 v[62:65], v[142:145], v[188:191], v[62:65]
	v_mfma_f32_16x16x32_bf16 v[58:61], v[164:167], v[188:191], v[58:61]
	v_mfma_f32_16x16x32_bf16 v[54:57], v[142:145], v[196:199], v[54:57]
	v_mfma_f32_16x16x32_bf16 v[46:49], v[164:167], v[196:199], v[46:49]
	v_mfma_f32_16x16x32_bf16 v[38:41], v[142:145], v[218:221], v[38:41]
	v_mfma_f32_16x16x32_bf16 v[30:33], v[164:167], v[218:221], v[30:33]
	v_mfma_f32_16x16x32_bf16 v[22:25], v[142:145], v[226:229], v[22:25]
	v_mfma_f32_16x16x32_bf16 v[14:17], v[164:167], v[226:229], v[14:17]
	v_mfma_f32_16x16x32_bf16 v[62:65], v[160:163], v[192:195], v[62:65]
	v_mfma_f32_16x16x32_bf16 v[58:61], v[168:171], v[192:195], v[58:61]
	v_mfma_f32_16x16x32_bf16 v[54:57], v[160:163], v[214:217], v[54:57]
	v_mfma_f32_16x16x32_bf16 v[46:49], v[168:171], v[214:217], v[46:49]
	v_mfma_f32_16x16x32_bf16 v[38:41], v[160:163], v[222:225], v[38:41]
	v_mfma_f32_16x16x32_bf16 v[30:33], v[168:171], v[222:225], v[30:33]
	v_mfma_f32_16x16x32_bf16 v[22:25], v[160:163], v[230:233], v[22:25]
	v_mfma_f32_16x16x32_bf16 v[14:17], v[168:171], v[230:233], v[14:17]
	s_setprio 0
	s_lshl_b32 s98, s70, 8
	s_cmp_ge_i32 s98, s35
	s_cbranch_scc1 .Lgate_skip_3
	s_setprio 1
	v_mfma_f32_16x16x32_bf16 v[50:53], v[172:175], v[188:191], v[50:53]
	v_mfma_f32_16x16x32_bf16 v[42:45], v[180:183], v[188:191], v[42:45]
	v_mfma_f32_16x16x32_bf16 v[34:37], v[172:175], v[196:199], v[34:37]
	v_mfma_f32_16x16x32_bf16 v[26:29], v[180:183], v[196:199], v[26:29]
	v_mfma_f32_16x16x32_bf16 v[18:21], v[172:175], v[218:221], v[18:21]
	v_mfma_f32_16x16x32_bf16 v[10:13], v[180:183], v[218:221], v[10:13]
	v_mfma_f32_16x16x32_bf16 v[6:9], v[172:175], v[226:229], v[6:9]
	v_mfma_f32_16x16x32_bf16 v[2:5], v[180:183], v[226:229], v[2:5]
	v_mfma_f32_16x16x32_bf16 v[50:53], v[176:179], v[192:195], v[50:53]
	v_mfma_f32_16x16x32_bf16 v[42:45], v[184:187], v[192:195], v[42:45]
	v_mfma_f32_16x16x32_bf16 v[34:37], v[176:179], v[214:217], v[34:37]
	v_mfma_f32_16x16x32_bf16 v[26:29], v[184:187], v[214:217], v[26:29]
	v_mfma_f32_16x16x32_bf16 v[18:21], v[176:179], v[222:225], v[18:21]
	v_mfma_f32_16x16x32_bf16 v[10:13], v[184:187], v[222:225], v[10:13]
	v_mfma_f32_16x16x32_bf16 v[6:9], v[176:179], v[230:233], v[6:9]
	v_mfma_f32_16x16x32_bf16 v[2:5], v[184:187], v[230:233], v[2:5]
.Lgate_skip_3:
	s_setprio 0
	s_barrier
	s_add_u32 s2, s2, 0x100
	s_addc_u32 s3, s3, 0
	s_add_u32 s34, s34, 0x100
	s_addc_u32 s72, s72, 0
	s_cmp_ge_u32 s73, s64
	s_mov_b32 s10, s73
	s_cbranch_scc0 .LBB0_639
	s_and_b64 vcc, exec, s[8:9]
	s_cbranch_vccz .LBB0_642
	s_barrier
